# v13 + prefetch loads ahead of the serialized sumsq loads (gate/up epilogue) and residual-x loads (out-proj epilogue)
# baseline (speedup 1.0000x reference)
;     DI void operator()(const AccT& acc, const Unit& u, int wr, int wc, int fr, int fq, LAS unsigned char* ldsx) const {
;     ...
;         f32x4 w0[2], w1[2], w2[2], cb[2];
; #pragma unroll
;         for (int n = 0; n < 2; ++n) { const int f = u.pn * 128 + wc * 32 + 16 * n + 4 * fq;
;             w0[n] = *(const f32x4*)(convw + f); w1[n] = *(const f32x4*)(convw + DFF + f); w2[n] = *(const f32x4*)(convw + 2 * DFF + f); cb[n] = *(const f32x4*)(convb + f); }
;         float rs[2][4];
; #pragma unroll
;         for (int ai = 0; ai < 2; ++ai)
; #pragma unroll
;             for (int m = 0; m < 4; ++m) { const int tok = tok0 + 128 * ai + 16 * m; const bool ok = tok >= 0 && tok < (prompt ? SEQ : MTOK);
;                 rs[ai][m] = ok ? rsqrtf(sumsq[ok ? tok : 0] * (1.f / DM) + EPS) : 0.f; }
.LBB0_833:
	v_lshl_or_b32 v216, s28, 7, v244
	v_ashrrev_i32_e32 v217, 31, v216
	v_lshlrev_b64 v[196:197], 2, v[216:217]
	v_or_b32_e32 v182, 16, v216
	v_lshl_add_u64 v[46:47], s[10:11], 0, v[196:197]
	v_lshl_add_u64 v[48:49], s[12:13], 0, v[196:197]
	v_ashrrev_i32_e32 v183, 31, v182
	global_load_dwordx4 v[124:127], v[46:47], off
	global_load_dwordx4 v[128:131], v[48:49], off
	v_lshlrev_b64 v[48:49], 2, v[182:183]
	v_lshl_add_u64 v[44:45], s[48:49], 0, v[196:197]
	v_lshl_add_u64 v[56:57], s[50:51], 0, v[196:197]
	v_lshl_add_u64 v[50:51], s[10:11], 0, v[48:49]
	v_lshl_add_u64 v[52:53], s[12:13], 0, v[48:49]
	global_load_dwordx4 v[132:135], v[44:45], off
	s_nop 0
	global_load_dwordx4 v[44:47], v[44:45], off offset:64
	s_nop 0
	global_load_dwordx4 v[48:51], v[50:51], off
	s_nop 0
	global_load_dwordx4 v[52:55], v[52:53], off
	s_nop 0
	global_load_dwordx4 v[136:139], v[56:57], off
	s_nop 0
	global_load_dwordx4 v[56:59], v[56:57], off offset:64
	v_add_u32_e32 v172, s29, v240
	v_cmp_gt_u32_e32 vcc, s23, v172
	v_mov_b32_e32 v210, 0
	v_mov_b32_e32 v214, 0
	v_min_u32_e32 v249, s23, v172
	v_lshlrev_b32_e32 v249, 2, v249
	global_load_dword v248, v249, s[58:59]
	v_add_u32_e32 v249, 16, v172
	v_min_u32_e32 v249, s23, v249
	v_lshlrev_b32_e32 v249, 2, v249
	global_load_dword v248, v249, s[58:59]
	v_add_u32_e32 v249, 32, v172
	v_min_u32_e32 v249, s23, v249
	v_lshlrev_b32_e32 v249, 2, v249
	global_load_dword v248, v249, s[58:59]
	v_add_u32_e32 v249, 48, v172
	v_min_u32_e32 v249, s23, v249
	v_lshlrev_b32_e32 v249, 2, v249
	global_load_dword v248, v249, s[58:59]
	v_add_u32_e32 v249, 128, v172
	v_min_u32_e32 v249, s23, v249
	v_lshlrev_b32_e32 v249, 2, v249
	global_load_dword v248, v249, s[58:59]
	v_add_u32_e32 v249, 144, v172
	v_min_u32_e32 v249, s23, v249
	v_lshlrev_b32_e32 v249, 2, v249
	global_load_dword v248, v249, s[58:59]
	v_add_u32_e32 v249, 160, v172
	v_min_u32_e32 v249, s23, v249
	v_lshlrev_b32_e32 v249, 2, v249
	global_load_dword v248, v249, s[58:59]
	v_add_u32_e32 v249, 176, v172
	v_min_u32_e32 v249, s23, v249
	v_lshlrev_b32_e32 v249, 2, v249
	global_load_dword v248, v249, s[58:59]
	s_and_saveexec_b64 s[28:29], vcc
	s_cbranch_execz .LBB0_835
	v_lshl_add_u64 v[160:161], v[172:173], 2, s[58:59]
	global_load_dword v160, v[160:161], off
	s_mov_b32 s30, 0x800000
	s_waitcnt vmcnt(0)
	v_fmamk_f32 v160, v160, 0x3a800000, v236
	v_mul_f32_e32 v161, 0x4b800000, v160
	v_cmp_gt_f32_e32 vcc, s30, v160
	s_nop 1
	v_cndmask_b32_e32 v160, v160, v161, vcc
	v_rsq_f32_e32 v160, v160
	s_nop 0
	v_mul_f32_e32 v161, 0x45800000, v160
	v_cndmask_b32_e32 v214, v160, v161, vcc

; #define LAS __attribute__((address_space(3)))
; DI u32x2 pk4(f32x4 v) { u32x2 r; r.x = pk2(v[0], v[1]); r.y = pk2(v[2], v[3]); return r; }
;     DI void operator()(const AccT& acc, const Unit& u, int wr, int wc, int fr, int fq, LAS unsigned char*) const {
;         const int col0 = u.pn * 256 + wc * 32 + 4 * fq;
; #pragma unroll
;         for (int ai = 0; ai < 2; ++ai)
; #pragma unroll
;             for (int m = 0; m < 4; ++m) {
;                 const int row = u.pm * 256 + ai * 128 + wr * 64 + m * 16 + fr;
;                 const float* xr = (row < SEQ ? xp + (size_t)row * DM : xs + (size_t)(row - SEQ) * DM) + col0;
;                 bf16_t* brow = X1B + (size_t)(row < SEQ ? row + 2 : row + (X1B_PROMPT_ROWS - SEQ)) * DM + col0;
;                 float ss = 0.f;
; #pragma unroll
;                 for (int bj = 0; bj < 2; ++bj)
; #pragma unroll
;                     for (int n = 0; n < 2; ++n) {
;                         const int c = bj * 128 + n * 16;
;                         const f32x4 o = *(const f32x4*)(xr + c) + acc[ai][bj][m][n];
;                         *(u32x2*)(brow + c) = pk4(o);
;                         ss += (o[0] * o[0] + o[1] * o[1]) + (o[2] * o[2] + o[3] * o[3]);
;                     }
;                 ss += __shfl_xor(ss, 16); ss += __shfl_xor(ss, 32);
;                 if (fq == 0) unsafeAtomicAdd(sumsq + row, ss);
;             }
.LBB0_960:
	v_lshl_add_u32 v130, s31, 8, v132
	v_add_u32_e32 v136, 0xffffc000, v130
	v_ashrrev_i32_e32 v131, 31, v130
	v_cmp_gt_i32_e32 vcc, s84, v130
	v_mov_b32_e32 v138, s47
	v_mov_b32_e32 v139, s45
	v_cndmask_b32_e32 v137, 0, v131, vcc
	v_cndmask_b32_e32 v136, v136, v130, vcc
	v_cndmask_b32_e32 v139, v138, v139, vcc
	v_mov_b32_e32 v138, s46
	v_mov_b32_e32 v140, s44
	v_lshl_or_b32 v128, s33, 8, v134
	v_cndmask_b32_e32 v138, v138, v140, vcc
	v_lshlrev_b64 v[136:137], 12, v[136:137]
	v_ashrrev_i32_e32 v129, 31, v128
	v_lshl_add_u64 v[136:137], v[138:139], 0, v[136:137]
	v_lshl_add_u64 v[140:141], v[128:129], 2, v[136:137]
	global_load_dwordx4 v[136:139], v[140:141], off
	v_cndmask_b32_e64 v142, v238, 2, vcc
	v_add_co_u32_e32 v248, vcc, 0x10000, v140
	s_nop 1
	v_addc_co_u32_e32 v249, vcc, 0, v141, vcc
	global_load_dword v250, v[248:249], off
	global_load_dword v250, v[248:249], off offset:64
	global_load_dword v250, v[248:249], off offset:512
	global_load_dword v250, v[248:249], off offset:576
	v_add_co_u32_e32 v248, vcc, 0x20000, v140
	s_nop 1
	v_addc_co_u32_e32 v249, vcc, 0, v141, vcc
	global_load_dword v250, v[248:249], off
	global_load_dword v250, v[248:249], off offset:64
	global_load_dword v250, v[248:249], off offset:512
	global_load_dword v250, v[248:249], off offset:576
	v_add_co_u32_e32 v248, vcc, 0x30000, v140
	s_nop 1
	v_addc_co_u32_e32 v249, vcc, 0, v141, vcc
	global_load_dword v250, v[248:249], off
	global_load_dword v250, v[248:249], off offset:64
	global_load_dword v250, v[248:249], off offset:512
	global_load_dword v250, v[248:249], off offset:576
	v_add_co_u32_e32 v248, vcc, 0x80000, v140
	s_nop 1
	v_addc_co_u32_e32 v249, vcc, 0, v141, vcc
	global_load_dword v250, v[248:249], off
	global_load_dword v250, v[248:249], off offset:64
	global_load_dword v250, v[248:249], off offset:512
	global_load_dword v250, v[248:249], off offset:576
	v_add_co_u32_e32 v248, vcc, 0x90000, v140
	s_nop 1
	v_addc_co_u32_e32 v249, vcc, 0, v141, vcc
	global_load_dword v250, v[248:249], off
	global_load_dword v250, v[248:249], off offset:64
	global_load_dword v250, v[248:249], off offset:512
	global_load_dword v250, v[248:249], off offset:576
	v_add_co_u32_e32 v248, vcc, 0xa0000, v140
	s_nop 1
	v_addc_co_u32_e32 v249, vcc, 0, v141, vcc
	global_load_dword v250, v[248:249], off
	global_load_dword v250, v[248:249], off offset:64
	global_load_dword v250, v[248:249], off offset:512
	global_load_dword v250, v[248:249], off offset:576
	v_add_co_u32_e32 v248, vcc, 0xb0000, v140
	s_nop 1
	v_addc_co_u32_e32 v249, vcc, 0, v141, vcc
	global_load_dword v250, v[248:249], off
	global_load_dword v250, v[248:249], off offset:64
	global_load_dword v250, v[248:249], off offset:512
	global_load_dword v250, v[248:249], off offset:576
	v_add_u32_e32 v142, v142, v130
	v_ashrrev_i32_e32 v143, 31, v142
	v_lshlrev_b64 v[142:143], 11, v[142:143]
	v_lshl_add_u64 v[142:143], s[56:57], 0, v[142:143]
	v_lshl_add_u64 v[142:143], v[128:129], 1, v[142:143]
	s_waitcnt vmcnt(0)
	v_pk_add_f32 v[138:139], v[126:127], v[138:139]
	v_pk_add_f32 v[136:137], v[124:125], v[136:137]
	v_cvt_pk_bf16_f32 v125, v138, v139
	v_cvt_pk_bf16_f32 v124, v136, v137
	global_store_dwordx2 v[142:143], v[124:125], off
	global_load_dwordx4 v[124:127], v[140:141], off offset:64
	v_mul_f32_e32 v137, v137, v137
	v_mul_f32_e32 v139, v139, v139
	v_fmac_f32_e32 v137, v136, v136
	v_fmac_f32_e32 v139, v138, v138
	v_add_f32_e32 v136, v137, v139
	s_waitcnt vmcnt(0)
	v_pk_add_f32 v[126:127], v[122:123], v[126:127]
	v_pk_add_f32 v[124:125], v[120:121], v[124:125]
	v_cvt_pk_bf16_f32 v121, v126, v127
	v_cvt_pk_bf16_f32 v120, v124, v125
	global_store_dwordx2 v[142:143], v[120:121], off offset:32
	global_load_dwordx4 v[120:123], v[140:141], off offset:512
	v_mul_f32_e32 v125, v125, v125
	v_mul_f32_e32 v127, v127, v127
	v_fmac_f32_e32 v125, v124, v124
	v_fmac_f32_e32 v127, v126, v126
	v_add_f32_e32 v124, v125, v127
	v_add_f32_e32 v124, v136, v124
	s_waitcnt vmcnt(0)
	v_pk_add_f32 v[122:123], v[118:119], v[122:123]
	v_pk_add_f32 v[144:145], v[116:117], v[120:121]
	v_cvt_pk_bf16_f32 v117, v122, v123
	v_cvt_pk_bf16_f32 v116, v144, v145
	global_store_dwordx2 v[142:143], v[116:117], off offset:256
	global_load_dwordx4 v[118:121], v[140:141], off offset:576
	v_and_b32_e32 v117, 64, v239
	v_mul_f32_e32 v125, v145, v145
	v_mul_f32_e32 v123, v123, v123
	v_xor_b32_e32 v116, 16, v239
	v_add_u32_e32 v117, 64, v117
	v_fmac_f32_e32 v125, v144, v144
	v_fmac_f32_e32 v123, v122, v122
	v_cmp_lt_i32_e32 vcc, v116, v117
	v_add_f32_e32 v122, v125, v123
	v_add_f32_e32 v122, v124, v122
	v_cndmask_b32_e32 v116, v239, v116, vcc
	v_lshlrev_b32_e32 v116, 2, v116
	s_waitcnt vmcnt(0)
	v_pk_add_f32 v[120:121], v[114:115], v[120:121]
	v_pk_add_f32 v[118:119], v[112:113], v[118:119]
	v_mul_f32_e32 v113, v121, v121
	v_mul_f32_e32 v112, v119, v119
	v_fmac_f32_e32 v112, v118, v118
	v_fmac_f32_e32 v113, v120, v120
	v_add_f32_e32 v112, v112, v113
	v_add_f32_e32 v112, v122, v112
	ds_bpermute_b32 v113, v116, v112
	v_xor_b32_e32 v114, 32, v239
	v_cmp_lt_i32_e32 vcc, v114, v117
	v_cvt_pk_bf16_f32 v118, v118, v119
	v_cvt_pk_bf16_f32 v119, v120, v121
	v_cndmask_b32_e32 v114, v239, v114, vcc
	v_lshlrev_b32_e32 v114, 2, v114
	s_waitcnt lgkmcnt(0)
	v_add_f32_e32 v112, v112, v113
	ds_bpermute_b32 v113, v114, v112
	global_store_dwordx2 v[142:143], v[118:119], off offset:288
	s_and_saveexec_b64 s[0:1], s[40:41]
	s_cbranch_execz .LBB0_962
	v_lshl_add_u64 v[118:119], v[130:131], 2, s[58:59]
	s_waitcnt lgkmcnt(0)
	v_add_f32_e32 v112, v112, v113
	global_atomic_add_f32 v[118:119], v112, off
